# rw3_e3_qp9
# speedup vs baseline: 1.0079x; 1.0079x over previous
; DI void phase_scans(const Params& p, const Grp& G, int layer, char* lds) {
;     ...
;   for (int t = blockIdx.x; t < ((nrw + 3) << sh); t += gridDim.x) {
;     const int kind = t >> sh, unit = t & ((1 << sh) - 1);
;     if (kind < nrw) { if (G.sample) rwkv_scan_task1(p, G, t, lds); else rwkv_scan_task(p, G, t, lds); }
;     else if (kind == nrw) chunk_scan_task<false>(p, G, layer, unit, lds);
;     else if (kind == nrw + 1) chunk_scan_task<true>(p, G, layer, unit, lds);
;     else s5_scan_task(p, G, layer, unit, lds);
;     __syncthreads();
.LBB0_579:
	s_or_b64 exec, exec, s[0:1]
	v_readlane_b32 s0, v254, 55
	s_cmp_ge_i32 s54, s0
	s_barrier
	s_cbranch_scc1 .LBB0_929
	v_readlane_b32 s0, v254, 54
	s_lshl_b32 s0, -1, s0
	s_not_b32 s0, s0
	v_readlane_b32 s91, v254, 21
	v_writelane_b32 v255, s0, 0
	v_readlane_b32 s0, v254, 56
	v_readlane_b32 s1, v254, 57
	s_lshl_b32 s1, s0, 7
	s_lshl_b32 s0, s0, 3
	v_writelane_b32 v255, s1, 1
	v_writelane_b32 v255, s0, 2
	s_branch .LBB0_582
.Lmy_task_exit:
	s_nop 0
.LBB0_581:
	s_add_i32 s91, s91, s92
	v_readlane_b32 s0, v254, 55
	s_cmp_ge_i32 s91, s0
	s_barrier
	s_cbranch_scc1 .LBB0_929

; DI float dpp_xor1(float x) { return __int_as_float(__builtin_amdgcn_mov_dpp(__float_as_int(x), 0xB1, 0xF, 0xF, true)); }
; DI float dpp_xor2(float x) { return __int_as_float(__builtin_amdgcn_mov_dpp(__float_as_int(x), 0x4E, 0xF, 0xF, true)); }
; DI float dpp_hm(float x) { return __int_as_float(__builtin_amdgcn_mov_dpp(__float_as_int(x), 0x141, 0xF, 0xF, true)); }
; DI float dpp_rm(float x) { return __int_as_float(__builtin_amdgcn_mov_dpp(__float_as_int(x), 0x140, 0xF, 0xF, true)); }
; DI void rwkv_scan_task(const Params& p, const Grp& G, int unit, char* lds) {
;     ...
;       for (int st = 0; st < 16; ++st) {
;         float4 kkB = kkA, wB = wA, kaB = kaA, kdB = kdA, rrB = rrA;
;         float vvB = vvA, uuB = uuA;
;         if (st < 15) {
;           const float* b = cur + (st + 1) * 384 + part * 4;
;           kkB = *(const float4*)(b + 3 * 64); wB = *(const float4*)(b + 1 * 64); kaB = *(const float4*)(b + 4 * 64);
;           kdB = *(const float4*)(b + 2 * 64); rrB = *(const float4*)(b);
;           vvB = cur[(st + 1) * 384 + 5 * 64 + vrow];
;           uuB = cur[(st + 1) * 384 + 5 * 64 + vrow + 4];
;         }
;         float ra = (S0 * kkA.x + S1 * kkA.y) + (S2 * kkA.z + S3 * kkA.w);
;         float rb = (T0 * kkA.x + T1 * kkA.y) + (T2 * kkA.z + T3 * kkA.w);
;         float rc = ypA, rd = ypB;
;         ra += dpp_xor1(ra); rb += dpp_xor1(rb); rc += dpp_xor1(rc); rd += dpp_xor1(rd);
;         ra += dpp_xor2(ra); rb += dpp_xor2(rb); rc += dpp_xor2(rc); rd += dpp_xor2(rd);
;         ra += dpp_hm(ra); rb += dpp_hm(rb); rc += dpp_hm(rc); rd += dpp_hm(rd);
;         ra += dpp_rm(ra); rb += dpp_rm(rb); rc += dpp_rm(rc); rd += dpp_rm(rd);
;         if (st > 0) { ykeep = (part == st - 1) ? rc : ykeep; zkeep = (part == st - 1) ? rd : zkeep; }
;         const float sa = ra, sb = rb;
;         S0 = S0 * wA.x + (sa * kaA.x + vvA * kdA.x);
;         S1 = S1 * wA.y + (sa * kaA.y + vvA * kdA.y);
;         S2 = S2 * wA.z + (sa * kaA.z + vvA * kdA.z);
;         S3 = S3 * wA.w + (sa * kaA.w + vvA * kdA.w);
;         T0 = T0 * wA.x + (sb * kaA.x + uuA * kdA.x);
;         T1 = T1 * wA.y + (sb * kaA.y + uuA * kdA.y);
;         T2 = T2 * wA.z + (sb * kaA.z + uuA * kdA.z);
;         T3 = T3 * wA.w + (sb * kaA.w + uuA * kdA.w);
;         ypA = (S0 * rrA.x + S1 * rrA.y) + (S2 * rrA.z + S3 * rrA.w);
;         ypB = (T0 * rrA.x + T1 * rrA.y) + (T2 * rrA.z + T3 * rrA.w);
.LBB0_927:
	s_bitcmp1_b32 s42, 0
	s_cselect_b32 s42, 0x6000, 0
	v_lshl_or_b32 v18, v119, 2, s42
	v_lshl_add_u32 v152, v118, 2, s42
	ds_read_b128 v[32:35], v18 offset:768
	ds_read_b128 v[28:31], v18 offset:512
	ds_read_b32 v40, v152 offset:1280
	ds_read_b32 v42, v152 offset:1296
	ds_read_b128 v[24:27], v18 offset:256
	ds_read_b128 v[36:39], v18 offset:1024
	ds_read_b128 v[20:23], v18 offset:0
	s_waitcnt lgkmcnt(0)
	ds_read_b128 v[56:59], v18 offset:2304
	ds_read_b128 v[52:55], v18 offset:2048
	ds_read_b32 v64, v152 offset:2816
	ds_read_b32 v66, v152 offset:2832
	ds_read_b128 v[48:51], v18 offset:1792
	ds_read_b128 v[60:63], v18 offset:2560
	ds_read_b128 v[44:47], v18 offset:1536
	v_pk_mul_f32 v[84:85], v[128:129], v[32:33]
	v_pk_mul_f32 v[86:87], v[16:17], v[32:33]
	v_pk_fma_f32 v[84:85], v[130:131], v[34:35], v[84:85]
	v_pk_fma_f32 v[86:87], v[14:15], v[34:35], v[86:87]
	v_add_f32_e32 v68, v84, v85
	v_add_f32_e32 v70, v86, v87
	v_pk_mul_f32 v[76:77], v[28:29], v[40:41] op_sel_hi:[1,0]
	v_pk_mul_f32 v[80:81], v[28:29], v[42:43] op_sel_hi:[1,0]
	v_add_f32_dpp v68, v68, v68 quad_perm:[1,0,3,2] row_mask:0xf bank_mask:0xf bound_ctrl:1
	v_add_f32_dpp v70, v70, v70 quad_perm:[1,0,3,2] row_mask:0xf bank_mask:0xf bound_ctrl:1
	v_pk_mul_f32 v[78:79], v[30:31], v[40:41] op_sel_hi:[1,0]
	v_pk_mul_f32 v[82:83], v[30:31], v[42:43] op_sel_hi:[1,0]
	v_add_f32_dpp v68, v68, v68 quad_perm:[2,3,0,1] row_mask:0xf bank_mask:0xf bound_ctrl:1
	v_add_f32_dpp v70, v70, v70 quad_perm:[2,3,0,1] row_mask:0xf bank_mask:0xf bound_ctrl:1
	v_pk_fma_f32 v[76:77], v[128:129], v[24:25], v[76:77]
	v_pk_fma_f32 v[80:81], v[16:17], v[24:25], v[80:81]
	v_add_f32_dpp v68, v68, v68 row_half_mirror row_mask:0xf bank_mask:0xf bound_ctrl:1
	v_add_f32_dpp v70, v70, v70 row_half_mirror row_mask:0xf bank_mask:0xf bound_ctrl:1
	v_pk_fma_f32 v[78:79], v[130:131], v[26:27], v[78:79]
	v_pk_fma_f32 v[82:83], v[14:15], v[26:27], v[82:83]
	v_add_f32_dpp v68, v68, v68 row_mirror row_mask:0xf bank_mask:0xf bound_ctrl:1
	v_add_f32_dpp v70, v70, v70 row_mirror row_mask:0xf bank_mask:0xf bound_ctrl:1
	v_pk_fma_f32 v[128:129], v[36:37], v[68:69], v[76:77] op_sel_hi:[1,0,1]
	v_pk_fma_f32 v[16:17], v[36:37], v[70:71], v[80:81] op_sel_hi:[1,0,1]
	v_pk_fma_f32 v[130:131], v[38:39], v[68:69], v[78:79] op_sel_hi:[1,0,1]
	v_pk_fma_f32 v[14:15], v[38:39], v[70:71], v[82:83] op_sel_hi:[1,0,1]
	v_pk_mul_f32 v[84:85], v[128:129], v[20:21]
	v_pk_mul_f32 v[86:87], v[16:17], v[20:21]
	v_pk_fma_f32 v[84:85], v[130:131], v[22:23], v[84:85]
	v_pk_fma_f32 v[86:87], v[14:15], v[22:23], v[86:87]
	v_add_f32_e32 v92, v84, v85
	v_add_f32_e32 v108, v86, v87
	s_waitcnt lgkmcnt(0)
	ds_read_b128 v[32:35], v18 offset:3840
	ds_read_b128 v[28:31], v18 offset:3584
	ds_read_b32 v40, v152 offset:4352
	ds_read_b32 v42, v152 offset:4368
	ds_read_b128 v[24:27], v18 offset:3328
	ds_read_b128 v[36:39], v18 offset:4096
	ds_read_b128 v[20:23], v18 offset:3072
	v_pk_mul_f32 v[84:85], v[128:129], v[56:57]
	v_pk_mul_f32 v[86:87], v[16:17], v[56:57]
	v_pk_fma_f32 v[84:85], v[130:131], v[58:59], v[84:85]
	v_pk_fma_f32 v[86:87], v[14:15], v[58:59], v[86:87]
	v_add_f32_e32 v68, v84, v85
	v_add_f32_e32 v70, v86, v87
	v_pk_mul_f32 v[76:77], v[52:53], v[64:65] op_sel_hi:[1,0]
	v_pk_mul_f32 v[80:81], v[52:53], v[66:67] op_sel_hi:[1,0]
	v_add_f32_dpp v68, v68, v68 quad_perm:[1,0,3,2] row_mask:0xf bank_mask:0xf bound_ctrl:1
	v_add_f32_dpp v70, v70, v70 quad_perm:[1,0,3,2] row_mask:0xf bank_mask:0xf bound_ctrl:1
	v_pk_mul_f32 v[78:79], v[54:55], v[64:65] op_sel_hi:[1,0]
	v_pk_mul_f32 v[82:83], v[54:55], v[66:67] op_sel_hi:[1,0]
	v_add_f32_dpp v68, v68, v68 quad_perm:[2,3,0,1] row_mask:0xf bank_mask:0xf bound_ctrl:1
	v_add_f32_dpp v70, v70, v70 quad_perm:[2,3,0,1] row_mask:0xf bank_mask:0xf bound_ctrl:1
	v_pk_fma_f32 v[76:77], v[128:129], v[48:49], v[76:77]
	v_pk_fma_f32 v[80:81], v[16:17], v[48:49], v[80:81]
	v_add_f32_dpp v68, v68, v68 row_half_mirror row_mask:0xf bank_mask:0xf bound_ctrl:1
	v_add_f32_dpp v70, v70, v70 row_half_mirror row_mask:0xf bank_mask:0xf bound_ctrl:1
	v_pk_fma_f32 v[78:79], v[130:131], v[50:51], v[78:79]
	v_pk_fma_f32 v[82:83], v[14:15], v[50:51], v[82:83]
	v_add_f32_dpp v68, v68, v68 row_mirror row_mask:0xf bank_mask:0xf bound_ctrl:1
	v_add_f32_dpp v70, v70, v70 row_mirror row_mask:0xf bank_mask:0xf bound_ctrl:1
	v_pk_fma_f32 v[128:129], v[60:61], v[68:69], v[76:77] op_sel_hi:[1,0,1]
	v_pk_fma_f32 v[16:17], v[60:61], v[70:71], v[80:81] op_sel_hi:[1,0,1]
	v_pk_fma_f32 v[130:131], v[62:63], v[68:69], v[78:79] op_sel_hi:[1,0,1]
	v_pk_fma_f32 v[14:15], v[62:63], v[70:71], v[82:83] op_sel_hi:[1,0,1]
	v_pk_mul_f32 v[84:85], v[128:129], v[44:45]
	v_pk_mul_f32 v[86:87], v[16:17], v[44:45]
	v_pk_fma_f32 v[84:85], v[130:131], v[46:47], v[84:85]
	v_pk_fma_f32 v[86:87], v[14:15], v[46:47], v[86:87]
	v_add_f32_e32 v93, v84, v85
	v_add_f32_e32 v109, v86, v87
	s_waitcnt lgkmcnt(0)
; DI float dpp_xor1(float x) { return __int_as_float(__builtin_amdgcn_mov_dpp(__float_as_int(x), 0xB1, 0xF, 0xF, true)); }
; DI float dpp_xor2(float x) { return __int_as_float(__builtin_amdgcn_mov_dpp(__float_as_int(x), 0x4E, 0xF, 0xF, true)); }
; DI float dpp_hm(float x) { return __int_as_float(__builtin_amdgcn_mov_dpp(__float_as_int(x), 0x141, 0xF, 0xF, true)); }
; DI float dpp_rm(float x) { return __int_as_float(__builtin_amdgcn_mov_dpp(__float_as_int(x), 0x140, 0xF, 0xF, true)); }
; DI void rwkv_scan_task(const Params& p, const Grp& G, int unit, char* lds) {
;     ...
;       for (int st = 0; st < 16; ++st) {
;         float4 kkB = kkA, wB = wA, kaB = kaA, kdB = kdA, rrB = rrA;
;         float vvB = vvA, uuB = uuA;
;         if (st < 15) {
;           const float* b = cur + (st + 1) * 384 + part * 4;
;           kkB = *(const float4*)(b + 3 * 64); wB = *(const float4*)(b + 1 * 64); kaB = *(const float4*)(b + 4 * 64);
;           kdB = *(const float4*)(b + 2 * 64); rrB = *(const float4*)(b);
;           vvB = cur[(st + 1) * 384 + 5 * 64 + vrow];
;           uuB = cur[(st + 1) * 384 + 5 * 64 + vrow + 4];
;         }
;         float ra = (S0 * kkA.x + S1 * kkA.y) + (S2 * kkA.z + S3 * kkA.w);
;         float rb = (T0 * kkA.x + T1 * kkA.y) + (T2 * kkA.z + T3 * kkA.w);
;         float rc = ypA, rd = ypB;
;         ra += dpp_xor1(ra); rb += dpp_xor1(rb); rc += dpp_xor1(rc); rd += dpp_xor1(rd);
;         ra += dpp_xor2(ra); rb += dpp_xor2(rb); rc += dpp_xor2(rc); rd += dpp_xor2(rd);
;         ra += dpp_hm(ra); rb += dpp_hm(rb); rc += dpp_hm(rc); rd += dpp_hm(rd);
;         ra += dpp_rm(ra); rb += dpp_rm(rb); rc += dpp_rm(rc); rd += dpp_rm(rd);
;         if (st > 0) { ykeep = (part == st - 1) ? rc : ykeep; zkeep = (part == st - 1) ? rd : zkeep; }
;         const float sa = ra, sb = rb;
;         S0 = S0 * wA.x + (sa * kaA.x + vvA * kdA.x);
;         S1 = S1 * wA.y + (sa * kaA.y + vvA * kdA.y);
;         S2 = S2 * wA.z + (sa * kaA.z + vvA * kdA.z);
;         S3 = S3 * wA.w + (sa * kaA.w + vvA * kdA.w);
;         T0 = T0 * wA.x + (sb * kaA.x + uuA * kdA.x);
;         T1 = T1 * wA.y + (sb * kaA.y + uuA * kdA.y);
;         T2 = T2 * wA.z + (sb * kaA.z + uuA * kdA.z);
;         T3 = T3 * wA.w + (sb * kaA.w + uuA * kdA.w);
;         ypA = (S0 * rrA.x + S1 * rrA.y) + (S2 * rrA.z + S3 * rrA.w);
;         ypB = (T0 * rrA.x + T1 * rrA.y) + (T2 * rrA.z + T3 * rrA.w);
	ds_read_b128 v[56:59], v18 offset:5376
	ds_read_b128 v[52:55], v18 offset:5120
	ds_read_b32 v64, v152 offset:5888
	ds_read_b32 v66, v152 offset:5904
	ds_read_b128 v[48:51], v18 offset:4864
	ds_read_b128 v[60:63], v18 offset:5632
	ds_read_b128 v[44:47], v18 offset:4608
	v_pk_mul_f32 v[84:85], v[128:129], v[32:33]
	v_pk_mul_f32 v[86:87], v[16:17], v[32:33]
	v_pk_fma_f32 v[84:85], v[130:131], v[34:35], v[84:85]
	v_pk_fma_f32 v[86:87], v[14:15], v[34:35], v[86:87]
	v_add_f32_e32 v68, v84, v85
	v_add_f32_e32 v70, v86, v87
	v_pk_mul_f32 v[76:77], v[28:29], v[40:41] op_sel_hi:[1,0]
	v_pk_mul_f32 v[80:81], v[28:29], v[42:43] op_sel_hi:[1,0]
	v_add_f32_dpp v68, v68, v68 quad_perm:[1,0,3,2] row_mask:0xf bank_mask:0xf bound_ctrl:1
	v_add_f32_dpp v70, v70, v70 quad_perm:[1,0,3,2] row_mask:0xf bank_mask:0xf bound_ctrl:1
	v_pk_mul_f32 v[78:79], v[30:31], v[40:41] op_sel_hi:[1,0]
	v_pk_mul_f32 v[82:83], v[30:31], v[42:43] op_sel_hi:[1,0]
	v_add_f32_dpp v68, v68, v68 quad_perm:[2,3,0,1] row_mask:0xf bank_mask:0xf bound_ctrl:1
	v_add_f32_dpp v70, v70, v70 quad_perm:[2,3,0,1] row_mask:0xf bank_mask:0xf bound_ctrl:1
	v_pk_fma_f32 v[76:77], v[128:129], v[24:25], v[76:77]
	v_pk_fma_f32 v[80:81], v[16:17], v[24:25], v[80:81]
	v_add_f32_dpp v68, v68, v68 row_half_mirror row_mask:0xf bank_mask:0xf bound_ctrl:1
	v_add_f32_dpp v70, v70, v70 row_half_mirror row_mask:0xf bank_mask:0xf bound_ctrl:1
	v_pk_fma_f32 v[78:79], v[130:131], v[26:27], v[78:79]
	v_pk_fma_f32 v[82:83], v[14:15], v[26:27], v[82:83]
	v_add_f32_dpp v68, v68, v68 row_mirror row_mask:0xf bank_mask:0xf bound_ctrl:1
	v_add_f32_dpp v70, v70, v70 row_mirror row_mask:0xf bank_mask:0xf bound_ctrl:1
	v_pk_fma_f32 v[128:129], v[36:37], v[68:69], v[76:77] op_sel_hi:[1,0,1]
	v_pk_fma_f32 v[16:17], v[36:37], v[70:71], v[80:81] op_sel_hi:[1,0,1]
	v_pk_fma_f32 v[130:131], v[38:39], v[68:69], v[78:79] op_sel_hi:[1,0,1]
	v_pk_fma_f32 v[14:15], v[38:39], v[70:71], v[82:83] op_sel_hi:[1,0,1]
	v_pk_mul_f32 v[84:85], v[128:129], v[20:21]
	v_pk_mul_f32 v[86:87], v[16:17], v[20:21]
	v_pk_fma_f32 v[84:85], v[130:131], v[22:23], v[84:85]
	v_pk_fma_f32 v[86:87], v[14:15], v[22:23], v[86:87]
	v_add_f32_e32 v94, v84, v85
	v_add_f32_e32 v110, v86, v87
	s_waitcnt lgkmcnt(0)
	ds_read_b128 v[32:35], v18 offset:6912
	ds_read_b128 v[28:31], v18 offset:6656
	ds_read_b32 v40, v152 offset:7424
	ds_read_b32 v42, v152 offset:7440
	ds_read_b128 v[24:27], v18 offset:6400
	ds_read_b128 v[36:39], v18 offset:7168
	ds_read_b128 v[20:23], v18 offset:6144
	v_pk_mul_f32 v[84:85], v[128:129], v[56:57]
	v_pk_mul_f32 v[86:87], v[16:17], v[56:57]
	v_pk_fma_f32 v[84:85], v[130:131], v[58:59], v[84:85]
	v_pk_fma_f32 v[86:87], v[14:15], v[58:59], v[86:87]
	v_add_f32_e32 v68, v84, v85
	v_add_f32_e32 v70, v86, v87
	v_pk_mul_f32 v[76:77], v[52:53], v[64:65] op_sel_hi:[1,0]
	v_pk_mul_f32 v[80:81], v[52:53], v[66:67] op_sel_hi:[1,0]
	v_add_f32_dpp v68, v68, v68 quad_perm:[1,0,3,2] row_mask:0xf bank_mask:0xf bound_ctrl:1
	v_add_f32_dpp v70, v70, v70 quad_perm:[1,0,3,2] row_mask:0xf bank_mask:0xf bound_ctrl:1
	v_pk_mul_f32 v[78:79], v[54:55], v[64:65] op_sel_hi:[1,0]
	v_pk_mul_f32 v[82:83], v[54:55], v[66:67] op_sel_hi:[1,0]
	v_add_f32_dpp v68, v68, v68 quad_perm:[2,3,0,1] row_mask:0xf bank_mask:0xf bound_ctrl:1
	v_add_f32_dpp v70, v70, v70 quad_perm:[2,3,0,1] row_mask:0xf bank_mask:0xf bound_ctrl:1
	v_pk_fma_f32 v[76:77], v[128:129], v[48:49], v[76:77]
	v_pk_fma_f32 v[80:81], v[16:17], v[48:49], v[80:81]
	v_add_f32_dpp v68, v68, v68 row_half_mirror row_mask:0xf bank_mask:0xf bound_ctrl:1
	v_add_f32_dpp v70, v70, v70 row_half_mirror row_mask:0xf bank_mask:0xf bound_ctrl:1
	v_pk_fma_f32 v[78:79], v[130:131], v[50:51], v[78:79]
	v_pk_fma_f32 v[82:83], v[14:15], v[50:51], v[82:83]
	v_add_f32_dpp v68, v68, v68 row_mirror row_mask:0xf bank_mask:0xf bound_ctrl:1
	v_add_f32_dpp v70, v70, v70 row_mirror row_mask:0xf bank_mask:0xf bound_ctrl:1
	v_pk_fma_f32 v[128:129], v[60:61], v[68:69], v[76:77] op_sel_hi:[1,0,1]
	v_pk_fma_f32 v[16:17], v[60:61], v[70:71], v[80:81] op_sel_hi:[1,0,1]
	v_pk_fma_f32 v[130:131], v[62:63], v[68:69], v[78:79] op_sel_hi:[1,0,1]
	v_pk_fma_f32 v[14:15], v[62:63], v[70:71], v[82:83] op_sel_hi:[1,0,1]
	v_pk_mul_f32 v[84:85], v[128:129], v[44:45]
	v_pk_mul_f32 v[86:87], v[16:17], v[44:45]
	v_pk_fma_f32 v[84:85], v[130:131], v[46:47], v[84:85]
	v_pk_fma_f32 v[86:87], v[14:15], v[46:47], v[86:87]
	v_add_f32_e32 v95, v84, v85
	v_add_f32_e32 v111, v86, v87
	s_waitcnt lgkmcnt(0)
	ds_read_b128 v[56:59], v18 offset:8448
	ds_read_b128 v[52:55], v18 offset:8192
	ds_read_b32 v64, v152 offset:8960
	ds_read_b32 v66, v152 offset:8976
	ds_read_b128 v[48:51], v18 offset:7936
	ds_read_b128 v[60:63], v18 offset:8704
	ds_read_b128 v[44:47], v18 offset:7680
	v_pk_mul_f32 v[84:85], v[128:129], v[32:33]
	v_pk_mul_f32 v[86:87], v[16:17], v[32:33]
	v_pk_fma_f32 v[84:85], v[130:131], v[34:35], v[84:85]
	v_pk_fma_f32 v[86:87], v[14:15], v[34:35], v[86:87]
	v_add_f32_e32 v68, v84, v85
	v_add_f32_e32 v70, v86, v87
	v_pk_mul_f32 v[76:77], v[28:29], v[40:41] op_sel_hi:[1,0]
	v_pk_mul_f32 v[80:81], v[28:29], v[42:43] op_sel_hi:[1,0]
	v_add_f32_dpp v68, v68, v68 quad_perm:[1,0,3,2] row_mask:0xf bank_mask:0xf bound_ctrl:1
	v_add_f32_dpp v70, v70, v70 quad_perm:[1,0,3,2] row_mask:0xf bank_mask:0xf bound_ctrl:1
	v_pk_mul_f32 v[78:79], v[30:31], v[40:41] op_sel_hi:[1,0]
	v_pk_mul_f32 v[82:83], v[30:31], v[42:43] op_sel_hi:[1,0]
	v_add_f32_dpp v68, v68, v68 quad_perm:[2,3,0,1] row_mask:0xf bank_mask:0xf bound_ctrl:1
	v_add_f32_dpp v70, v70, v70 quad_perm:[2,3,0,1] row_mask:0xf bank_mask:0xf bound_ctrl:1
	v_pk_fma_f32 v[76:77], v[128:129], v[24:25], v[76:77]
	v_pk_fma_f32 v[80:81], v[16:17], v[24:25], v[80:81]
	v_add_f32_dpp v68, v68, v68 row_half_mirror row_mask:0xf bank_mask:0xf bound_ctrl:1
	v_add_f32_dpp v70, v70, v70 row_half_mirror row_mask:0xf bank_mask:0xf bound_ctrl:1
	v_pk_fma_f32 v[78:79], v[130:131], v[26:27], v[78:79]
	v_pk_fma_f32 v[82:83], v[14:15], v[26:27], v[82:83]
	v_add_f32_dpp v68, v68, v68 row_mirror row_mask:0xf bank_mask:0xf bound_ctrl:1
	v_add_f32_dpp v70, v70, v70 row_mirror row_mask:0xf bank_mask:0xf bound_ctrl:1
	v_pk_fma_f32 v[128:129], v[36:37], v[68:69], v[76:77] op_sel_hi:[1,0,1]
	v_pk_fma_f32 v[16:17], v[36:37], v[70:71], v[80:81] op_sel_hi:[1,0,1]
	v_pk_fma_f32 v[130:131], v[38:39], v[68:69], v[78:79] op_sel_hi:[1,0,1]
	v_pk_fma_f32 v[14:15], v[38:39], v[70:71], v[82:83] op_sel_hi:[1,0,1]
	v_pk_mul_f32 v[84:85], v[128:129], v[20:21]
	v_pk_mul_f32 v[86:87], v[16:17], v[20:21]
	v_pk_fma_f32 v[84:85], v[130:131], v[22:23], v[84:85]
	v_pk_fma_f32 v[86:87], v[14:15], v[22:23], v[86:87]
	v_add_f32_e32 v96, v84, v85
	v_add_f32_e32 v112, v86, v87
	s_waitcnt lgkmcnt(0)
; DI float dpp_xor1(float x) { return __int_as_float(__builtin_amdgcn_mov_dpp(__float_as_int(x), 0xB1, 0xF, 0xF, true)); }
; DI float dpp_xor2(float x) { return __int_as_float(__builtin_amdgcn_mov_dpp(__float_as_int(x), 0x4E, 0xF, 0xF, true)); }
; DI float dpp_hm(float x) { return __int_as_float(__builtin_amdgcn_mov_dpp(__float_as_int(x), 0x141, 0xF, 0xF, true)); }
; DI float dpp_rm(float x) { return __int_as_float(__builtin_amdgcn_mov_dpp(__float_as_int(x), 0x140, 0xF, 0xF, true)); }
; DI void rwkv_scan_task(const Params& p, const Grp& G, int unit, char* lds) {
;     ...
;       for (int st = 0; st < 16; ++st) {
;         float4 kkB = kkA, wB = wA, kaB = kaA, kdB = kdA, rrB = rrA;
;         float vvB = vvA, uuB = uuA;
;         if (st < 15) {
;           const float* b = cur + (st + 1) * 384 + part * 4;
;           kkB = *(const float4*)(b + 3 * 64); wB = *(const float4*)(b + 1 * 64); kaB = *(const float4*)(b + 4 * 64);
;           kdB = *(const float4*)(b + 2 * 64); rrB = *(const float4*)(b);
;           vvB = cur[(st + 1) * 384 + 5 * 64 + vrow];
;           uuB = cur[(st + 1) * 384 + 5 * 64 + vrow + 4];
;         }
;         float ra = (S0 * kkA.x + S1 * kkA.y) + (S2 * kkA.z + S3 * kkA.w);
;         float rb = (T0 * kkA.x + T1 * kkA.y) + (T2 * kkA.z + T3 * kkA.w);
;         float rc = ypA, rd = ypB;
;         ra += dpp_xor1(ra); rb += dpp_xor1(rb); rc += dpp_xor1(rc); rd += dpp_xor1(rd);
;         ra += dpp_xor2(ra); rb += dpp_xor2(rb); rc += dpp_xor2(rc); rd += dpp_xor2(rd);
;         ra += dpp_hm(ra); rb += dpp_hm(rb); rc += dpp_hm(rc); rd += dpp_hm(rd);
;         ra += dpp_rm(ra); rb += dpp_rm(rb); rc += dpp_rm(rc); rd += dpp_rm(rd);
;         if (st > 0) { ykeep = (part == st - 1) ? rc : ykeep; zkeep = (part == st - 1) ? rd : zkeep; }
;         const float sa = ra, sb = rb;
;         S0 = S0 * wA.x + (sa * kaA.x + vvA * kdA.x);
;         S1 = S1 * wA.y + (sa * kaA.y + vvA * kdA.y);
;         S2 = S2 * wA.z + (sa * kaA.z + vvA * kdA.z);
;         S3 = S3 * wA.w + (sa * kaA.w + vvA * kdA.w);
;         T0 = T0 * wA.x + (sb * kaA.x + uuA * kdA.x);
;         T1 = T1 * wA.y + (sb * kaA.y + uuA * kdA.y);
;         T2 = T2 * wA.z + (sb * kaA.z + uuA * kdA.z);
;         T3 = T3 * wA.w + (sb * kaA.w + uuA * kdA.w);
;         ypA = (S0 * rrA.x + S1 * rrA.y) + (S2 * rrA.z + S3 * rrA.w);
;         ypB = (T0 * rrA.x + T1 * rrA.y) + (T2 * rrA.z + T3 * rrA.w);
	ds_read_b128 v[32:35], v18 offset:9984
	ds_read_b128 v[28:31], v18 offset:9728
	ds_read_b32 v40, v152 offset:10496
	ds_read_b32 v42, v152 offset:10512
	ds_read_b128 v[24:27], v18 offset:9472
	ds_read_b128 v[36:39], v18 offset:10240
	ds_read_b128 v[20:23], v18 offset:9216
	v_pk_mul_f32 v[84:85], v[128:129], v[56:57]
	v_pk_mul_f32 v[86:87], v[16:17], v[56:57]
	v_pk_fma_f32 v[84:85], v[130:131], v[58:59], v[84:85]
	v_pk_fma_f32 v[86:87], v[14:15], v[58:59], v[86:87]
	v_add_f32_e32 v68, v84, v85
	v_add_f32_e32 v70, v86, v87
	v_pk_mul_f32 v[76:77], v[52:53], v[64:65] op_sel_hi:[1,0]
	v_pk_mul_f32 v[80:81], v[52:53], v[66:67] op_sel_hi:[1,0]
	v_add_f32_dpp v68, v68, v68 quad_perm:[1,0,3,2] row_mask:0xf bank_mask:0xf bound_ctrl:1
	v_add_f32_dpp v70, v70, v70 quad_perm:[1,0,3,2] row_mask:0xf bank_mask:0xf bound_ctrl:1
	v_pk_mul_f32 v[78:79], v[54:55], v[64:65] op_sel_hi:[1,0]
	v_pk_mul_f32 v[82:83], v[54:55], v[66:67] op_sel_hi:[1,0]
	v_add_f32_dpp v68, v68, v68 quad_perm:[2,3,0,1] row_mask:0xf bank_mask:0xf bound_ctrl:1
	v_add_f32_dpp v70, v70, v70 quad_perm:[2,3,0,1] row_mask:0xf bank_mask:0xf bound_ctrl:1
	v_pk_fma_f32 v[76:77], v[128:129], v[48:49], v[76:77]
	v_pk_fma_f32 v[80:81], v[16:17], v[48:49], v[80:81]
	v_add_f32_dpp v68, v68, v68 row_half_mirror row_mask:0xf bank_mask:0xf bound_ctrl:1
	v_add_f32_dpp v70, v70, v70 row_half_mirror row_mask:0xf bank_mask:0xf bound_ctrl:1
	v_pk_fma_f32 v[78:79], v[130:131], v[50:51], v[78:79]
	v_pk_fma_f32 v[82:83], v[14:15], v[50:51], v[82:83]
	v_add_f32_dpp v68, v68, v68 row_mirror row_mask:0xf bank_mask:0xf bound_ctrl:1
	v_add_f32_dpp v70, v70, v70 row_mirror row_mask:0xf bank_mask:0xf bound_ctrl:1
	v_pk_fma_f32 v[128:129], v[60:61], v[68:69], v[76:77] op_sel_hi:[1,0,1]
	v_pk_fma_f32 v[16:17], v[60:61], v[70:71], v[80:81] op_sel_hi:[1,0,1]
	v_pk_fma_f32 v[130:131], v[62:63], v[68:69], v[78:79] op_sel_hi:[1,0,1]
	v_pk_fma_f32 v[14:15], v[62:63], v[70:71], v[82:83] op_sel_hi:[1,0,1]
	v_pk_mul_f32 v[84:85], v[128:129], v[44:45]
	v_pk_mul_f32 v[86:87], v[16:17], v[44:45]
	v_pk_fma_f32 v[84:85], v[130:131], v[46:47], v[84:85]
	v_pk_fma_f32 v[86:87], v[14:15], v[46:47], v[86:87]
	v_add_f32_e32 v97, v84, v85
	v_add_f32_e32 v113, v86, v87
	s_waitcnt lgkmcnt(0)
	ds_read_b128 v[56:59], v18 offset:11520
	ds_read_b128 v[52:55], v18 offset:11264
	ds_read_b32 v64, v152 offset:12032
	ds_read_b32 v66, v152 offset:12048
	ds_read_b128 v[48:51], v18 offset:11008
	ds_read_b128 v[60:63], v18 offset:11776
	ds_read_b128 v[44:47], v18 offset:10752
	v_pk_mul_f32 v[84:85], v[128:129], v[32:33]
	v_pk_mul_f32 v[86:87], v[16:17], v[32:33]
	v_pk_fma_f32 v[84:85], v[130:131], v[34:35], v[84:85]
	v_pk_fma_f32 v[86:87], v[14:15], v[34:35], v[86:87]
	v_add_f32_e32 v68, v84, v85
	v_add_f32_e32 v70, v86, v87
	v_pk_mul_f32 v[76:77], v[28:29], v[40:41] op_sel_hi:[1,0]
	v_pk_mul_f32 v[80:81], v[28:29], v[42:43] op_sel_hi:[1,0]
	v_add_f32_dpp v68, v68, v68 quad_perm:[1,0,3,2] row_mask:0xf bank_mask:0xf bound_ctrl:1
	v_add_f32_dpp v70, v70, v70 quad_perm:[1,0,3,2] row_mask:0xf bank_mask:0xf bound_ctrl:1
	v_pk_mul_f32 v[78:79], v[30:31], v[40:41] op_sel_hi:[1,0]
	v_pk_mul_f32 v[82:83], v[30:31], v[42:43] op_sel_hi:[1,0]
	v_add_f32_dpp v68, v68, v68 quad_perm:[2,3,0,1] row_mask:0xf bank_mask:0xf bound_ctrl:1
	v_add_f32_dpp v70, v70, v70 quad_perm:[2,3,0,1] row_mask:0xf bank_mask:0xf bound_ctrl:1
	v_pk_fma_f32 v[76:77], v[128:129], v[24:25], v[76:77]
	v_pk_fma_f32 v[80:81], v[16:17], v[24:25], v[80:81]
	v_add_f32_dpp v68, v68, v68 row_half_mirror row_mask:0xf bank_mask:0xf bound_ctrl:1
	v_add_f32_dpp v70, v70, v70 row_half_mirror row_mask:0xf bank_mask:0xf bound_ctrl:1
	v_pk_fma_f32 v[78:79], v[130:131], v[26:27], v[78:79]
	v_pk_fma_f32 v[82:83], v[14:15], v[26:27], v[82:83]
	v_add_f32_dpp v68, v68, v68 row_mirror row_mask:0xf bank_mask:0xf bound_ctrl:1
	v_add_f32_dpp v70, v70, v70 row_mirror row_mask:0xf bank_mask:0xf bound_ctrl:1
	v_pk_fma_f32 v[128:129], v[36:37], v[68:69], v[76:77] op_sel_hi:[1,0,1]
	v_pk_fma_f32 v[16:17], v[36:37], v[70:71], v[80:81] op_sel_hi:[1,0,1]
	v_pk_fma_f32 v[130:131], v[38:39], v[68:69], v[78:79] op_sel_hi:[1,0,1]
	v_pk_fma_f32 v[14:15], v[38:39], v[70:71], v[82:83] op_sel_hi:[1,0,1]
	v_pk_mul_f32 v[84:85], v[128:129], v[20:21]
	v_pk_mul_f32 v[86:87], v[16:17], v[20:21]
	v_pk_fma_f32 v[84:85], v[130:131], v[22:23], v[84:85]
	v_pk_fma_f32 v[86:87], v[14:15], v[22:23], v[86:87]
	v_add_f32_e32 v98, v84, v85
	v_add_f32_e32 v114, v86, v87
	s_waitcnt lgkmcnt(0)
	ds_read_b128 v[32:35], v18 offset:13056
	ds_read_b128 v[28:31], v18 offset:12800
	ds_read_b32 v40, v152 offset:13568
	ds_read_b32 v42, v152 offset:13584
	ds_read_b128 v[24:27], v18 offset:12544
	ds_read_b128 v[36:39], v18 offset:13312
	ds_read_b128 v[20:23], v18 offset:12288
	v_pk_mul_f32 v[84:85], v[128:129], v[56:57]
	v_pk_mul_f32 v[86:87], v[16:17], v[56:57]
	v_pk_fma_f32 v[84:85], v[130:131], v[58:59], v[84:85]
	v_pk_fma_f32 v[86:87], v[14:15], v[58:59], v[86:87]
	v_add_f32_e32 v68, v84, v85
	v_add_f32_e32 v70, v86, v87
	v_pk_mul_f32 v[76:77], v[52:53], v[64:65] op_sel_hi:[1,0]
	v_pk_mul_f32 v[80:81], v[52:53], v[66:67] op_sel_hi:[1,0]
	v_add_f32_dpp v68, v68, v68 quad_perm:[1,0,3,2] row_mask:0xf bank_mask:0xf bound_ctrl:1
	v_add_f32_dpp v70, v70, v70 quad_perm:[1,0,3,2] row_mask:0xf bank_mask:0xf bound_ctrl:1
	v_pk_mul_f32 v[78:79], v[54:55], v[64:65] op_sel_hi:[1,0]
	v_pk_mul_f32 v[82:83], v[54:55], v[66:67] op_sel_hi:[1,0]
	v_add_f32_dpp v68, v68, v68 quad_perm:[2,3,0,1] row_mask:0xf bank_mask:0xf bound_ctrl:1
	v_add_f32_dpp v70, v70, v70 quad_perm:[2,3,0,1] row_mask:0xf bank_mask:0xf bound_ctrl:1
	v_pk_fma_f32 v[76:77], v[128:129], v[48:49], v[76:77]
	v_pk_fma_f32 v[80:81], v[16:17], v[48:49], v[80:81]
	v_add_f32_dpp v68, v68, v68 row_half_mirror row_mask:0xf bank_mask:0xf bound_ctrl:1
	v_add_f32_dpp v70, v70, v70 row_half_mirror row_mask:0xf bank_mask:0xf bound_ctrl:1
	v_pk_fma_f32 v[78:79], v[130:131], v[50:51], v[78:79]
	v_pk_fma_f32 v[82:83], v[14:15], v[50:51], v[82:83]
	v_add_f32_dpp v68, v68, v68 row_mirror row_mask:0xf bank_mask:0xf bound_ctrl:1
	v_add_f32_dpp v70, v70, v70 row_mirror row_mask:0xf bank_mask:0xf bound_ctrl:1
	v_pk_fma_f32 v[128:129], v[60:61], v[68:69], v[76:77] op_sel_hi:[1,0,1]
	v_pk_fma_f32 v[16:17], v[60:61], v[70:71], v[80:81] op_sel_hi:[1,0,1]
	v_pk_fma_f32 v[130:131], v[62:63], v[68:69], v[78:79] op_sel_hi:[1,0,1]
	v_pk_fma_f32 v[14:15], v[62:63], v[70:71], v[82:83] op_sel_hi:[1,0,1]
	v_pk_mul_f32 v[84:85], v[128:129], v[44:45]
	v_pk_mul_f32 v[86:87], v[16:17], v[44:45]
	v_pk_fma_f32 v[84:85], v[130:131], v[46:47], v[84:85]
	v_pk_fma_f32 v[86:87], v[14:15], v[46:47], v[86:87]
	v_add_f32_e32 v99, v84, v85
	v_add_f32_e32 v115, v86, v87
	s_waitcnt lgkmcnt(0)
; DI float dpp_xor1(float x) { return __int_as_float(__builtin_amdgcn_mov_dpp(__float_as_int(x), 0xB1, 0xF, 0xF, true)); }
; DI float dpp_xor2(float x) { return __int_as_float(__builtin_amdgcn_mov_dpp(__float_as_int(x), 0x4E, 0xF, 0xF, true)); }
; DI float dpp_hm(float x) { return __int_as_float(__builtin_amdgcn_mov_dpp(__float_as_int(x), 0x141, 0xF, 0xF, true)); }
; DI float dpp_rm(float x) { return __int_as_float(__builtin_amdgcn_mov_dpp(__float_as_int(x), 0x140, 0xF, 0xF, true)); }
; DI void rwkv_scan_task(const Params& p, const Grp& G, int unit, char* lds) {
;     ...
;       for (int st = 0; st < 16; ++st) {
;         float4 kkB = kkA, wB = wA, kaB = kaA, kdB = kdA, rrB = rrA;
;         float vvB = vvA, uuB = uuA;
;         if (st < 15) {
;           const float* b = cur + (st + 1) * 384 + part * 4;
;           kkB = *(const float4*)(b + 3 * 64); wB = *(const float4*)(b + 1 * 64); kaB = *(const float4*)(b + 4 * 64);
;           kdB = *(const float4*)(b + 2 * 64); rrB = *(const float4*)(b);
;           vvB = cur[(st + 1) * 384 + 5 * 64 + vrow];
;           uuB = cur[(st + 1) * 384 + 5 * 64 + vrow + 4];
;         }
;         float ra = (S0 * kkA.x + S1 * kkA.y) + (S2 * kkA.z + S3 * kkA.w);
;         float rb = (T0 * kkA.x + T1 * kkA.y) + (T2 * kkA.z + T3 * kkA.w);
;         float rc = ypA, rd = ypB;
;         ra += dpp_xor1(ra); rb += dpp_xor1(rb); rc += dpp_xor1(rc); rd += dpp_xor1(rd);
;         ra += dpp_xor2(ra); rb += dpp_xor2(rb); rc += dpp_xor2(rc); rd += dpp_xor2(rd);
;         ra += dpp_hm(ra); rb += dpp_hm(rb); rc += dpp_hm(rc); rd += dpp_hm(rd);
;         ra += dpp_rm(ra); rb += dpp_rm(rb); rc += dpp_rm(rc); rd += dpp_rm(rd);
;         if (st > 0) { ykeep = (part == st - 1) ? rc : ykeep; zkeep = (part == st - 1) ? rd : zkeep; }
;         const float sa = ra, sb = rb;
;         S0 = S0 * wA.x + (sa * kaA.x + vvA * kdA.x);
;         S1 = S1 * wA.y + (sa * kaA.y + vvA * kdA.y);
;         S2 = S2 * wA.z + (sa * kaA.z + vvA * kdA.z);
;         S3 = S3 * wA.w + (sa * kaA.w + vvA * kdA.w);
;         T0 = T0 * wA.x + (sb * kaA.x + uuA * kdA.x);
;         T1 = T1 * wA.y + (sb * kaA.y + uuA * kdA.y);
;         T2 = T2 * wA.z + (sb * kaA.z + uuA * kdA.z);
;         T3 = T3 * wA.w + (sb * kaA.w + uuA * kdA.w);
;         ypA = (S0 * rrA.x + S1 * rrA.y) + (S2 * rrA.z + S3 * rrA.w);
;         ypB = (T0 * rrA.x + T1 * rrA.y) + (T2 * rrA.z + T3 * rrA.w);
	ds_read_b128 v[56:59], v18 offset:14592
	ds_read_b128 v[52:55], v18 offset:14336
	ds_read_b32 v64, v152 offset:15104
	ds_read_b32 v66, v152 offset:15120
	ds_read_b128 v[48:51], v18 offset:14080
	ds_read_b128 v[60:63], v18 offset:14848
	ds_read_b128 v[44:47], v18 offset:13824
	v_pk_mul_f32 v[84:85], v[128:129], v[32:33]
	v_pk_mul_f32 v[86:87], v[16:17], v[32:33]
	v_pk_fma_f32 v[84:85], v[130:131], v[34:35], v[84:85]
	v_pk_fma_f32 v[86:87], v[14:15], v[34:35], v[86:87]
	v_add_f32_e32 v68, v84, v85
	v_add_f32_e32 v70, v86, v87
	v_pk_mul_f32 v[76:77], v[28:29], v[40:41] op_sel_hi:[1,0]
	v_pk_mul_f32 v[80:81], v[28:29], v[42:43] op_sel_hi:[1,0]
	v_add_f32_dpp v68, v68, v68 quad_perm:[1,0,3,2] row_mask:0xf bank_mask:0xf bound_ctrl:1
	v_add_f32_dpp v70, v70, v70 quad_perm:[1,0,3,2] row_mask:0xf bank_mask:0xf bound_ctrl:1
	v_pk_mul_f32 v[78:79], v[30:31], v[40:41] op_sel_hi:[1,0]
	v_pk_mul_f32 v[82:83], v[30:31], v[42:43] op_sel_hi:[1,0]
	v_add_f32_dpp v68, v68, v68 quad_perm:[2,3,0,1] row_mask:0xf bank_mask:0xf bound_ctrl:1
	v_add_f32_dpp v70, v70, v70 quad_perm:[2,3,0,1] row_mask:0xf bank_mask:0xf bound_ctrl:1
	v_pk_fma_f32 v[76:77], v[128:129], v[24:25], v[76:77]
	v_pk_fma_f32 v[80:81], v[16:17], v[24:25], v[80:81]
	v_add_f32_dpp v68, v68, v68 row_half_mirror row_mask:0xf bank_mask:0xf bound_ctrl:1
	v_add_f32_dpp v70, v70, v70 row_half_mirror row_mask:0xf bank_mask:0xf bound_ctrl:1
	v_pk_fma_f32 v[78:79], v[130:131], v[26:27], v[78:79]
	v_pk_fma_f32 v[82:83], v[14:15], v[26:27], v[82:83]
	v_add_f32_dpp v68, v68, v68 row_mirror row_mask:0xf bank_mask:0xf bound_ctrl:1
	v_add_f32_dpp v70, v70, v70 row_mirror row_mask:0xf bank_mask:0xf bound_ctrl:1
	v_pk_fma_f32 v[128:129], v[36:37], v[68:69], v[76:77] op_sel_hi:[1,0,1]
	v_pk_fma_f32 v[16:17], v[36:37], v[70:71], v[80:81] op_sel_hi:[1,0,1]
	v_pk_fma_f32 v[130:131], v[38:39], v[68:69], v[78:79] op_sel_hi:[1,0,1]
	v_pk_fma_f32 v[14:15], v[38:39], v[70:71], v[82:83] op_sel_hi:[1,0,1]
	v_pk_mul_f32 v[84:85], v[128:129], v[20:21]
	v_pk_mul_f32 v[86:87], v[16:17], v[20:21]
	v_pk_fma_f32 v[84:85], v[130:131], v[22:23], v[84:85]
	v_pk_fma_f32 v[86:87], v[14:15], v[22:23], v[86:87]
	v_add_f32_e32 v100, v84, v85
	v_add_f32_e32 v116, v86, v87
	s_waitcnt lgkmcnt(0)
	ds_read_b128 v[32:35], v18 offset:16128
	ds_read_b128 v[28:31], v18 offset:15872
	ds_read_b32 v40, v152 offset:16640
	ds_read_b32 v42, v152 offset:16656
	ds_read_b128 v[24:27], v18 offset:15616
	ds_read_b128 v[36:39], v18 offset:16384
	ds_read_b128 v[20:23], v18 offset:15360
	v_pk_mul_f32 v[84:85], v[128:129], v[56:57]
	v_pk_mul_f32 v[86:87], v[16:17], v[56:57]
	v_pk_fma_f32 v[84:85], v[130:131], v[58:59], v[84:85]
	v_pk_fma_f32 v[86:87], v[14:15], v[58:59], v[86:87]
	v_add_f32_e32 v68, v84, v85
	v_add_f32_e32 v70, v86, v87
	v_pk_mul_f32 v[76:77], v[52:53], v[64:65] op_sel_hi:[1,0]
	v_pk_mul_f32 v[80:81], v[52:53], v[66:67] op_sel_hi:[1,0]
	v_add_f32_dpp v68, v68, v68 quad_perm:[1,0,3,2] row_mask:0xf bank_mask:0xf bound_ctrl:1
	v_add_f32_dpp v70, v70, v70 quad_perm:[1,0,3,2] row_mask:0xf bank_mask:0xf bound_ctrl:1
	v_pk_mul_f32 v[78:79], v[54:55], v[64:65] op_sel_hi:[1,0]
	v_pk_mul_f32 v[82:83], v[54:55], v[66:67] op_sel_hi:[1,0]
	v_add_f32_dpp v68, v68, v68 quad_perm:[2,3,0,1] row_mask:0xf bank_mask:0xf bound_ctrl:1
	v_add_f32_dpp v70, v70, v70 quad_perm:[2,3,0,1] row_mask:0xf bank_mask:0xf bound_ctrl:1
	v_pk_fma_f32 v[76:77], v[128:129], v[48:49], v[76:77]
	v_pk_fma_f32 v[80:81], v[16:17], v[48:49], v[80:81]
	v_add_f32_dpp v68, v68, v68 row_half_mirror row_mask:0xf bank_mask:0xf bound_ctrl:1
	v_add_f32_dpp v70, v70, v70 row_half_mirror row_mask:0xf bank_mask:0xf bound_ctrl:1
	v_pk_fma_f32 v[78:79], v[130:131], v[50:51], v[78:79]
	v_pk_fma_f32 v[82:83], v[14:15], v[50:51], v[82:83]
	v_add_f32_dpp v68, v68, v68 row_mirror row_mask:0xf bank_mask:0xf bound_ctrl:1
	v_add_f32_dpp v70, v70, v70 row_mirror row_mask:0xf bank_mask:0xf bound_ctrl:1
	v_pk_fma_f32 v[128:129], v[60:61], v[68:69], v[76:77] op_sel_hi:[1,0,1]
	v_pk_fma_f32 v[16:17], v[60:61], v[70:71], v[80:81] op_sel_hi:[1,0,1]
	v_pk_fma_f32 v[130:131], v[62:63], v[68:69], v[78:79] op_sel_hi:[1,0,1]
	v_pk_fma_f32 v[14:15], v[62:63], v[70:71], v[82:83] op_sel_hi:[1,0,1]
	v_pk_mul_f32 v[84:85], v[128:129], v[44:45]
	v_pk_mul_f32 v[86:87], v[16:17], v[44:45]
	v_pk_fma_f32 v[84:85], v[130:131], v[46:47], v[84:85]
	v_pk_fma_f32 v[86:87], v[14:15], v[46:47], v[86:87]
	v_add_f32_e32 v101, v84, v85
	v_add_f32_e32 v117, v86, v87
	s_waitcnt lgkmcnt(0)
	ds_read_b128 v[56:59], v18 offset:17664
	ds_read_b128 v[52:55], v18 offset:17408
	ds_read_b32 v64, v152 offset:18176
	ds_read_b32 v66, v152 offset:18192
	ds_read_b128 v[48:51], v18 offset:17152
	ds_read_b128 v[60:63], v18 offset:17920
	ds_read_b128 v[44:47], v18 offset:16896
	v_pk_mul_f32 v[84:85], v[128:129], v[32:33]
	v_pk_mul_f32 v[86:87], v[16:17], v[32:33]
	v_pk_fma_f32 v[84:85], v[130:131], v[34:35], v[84:85]
	v_pk_fma_f32 v[86:87], v[14:15], v[34:35], v[86:87]
	v_add_f32_e32 v68, v84, v85
	v_add_f32_e32 v70, v86, v87
	v_pk_mul_f32 v[76:77], v[28:29], v[40:41] op_sel_hi:[1,0]
	v_pk_mul_f32 v[80:81], v[28:29], v[42:43] op_sel_hi:[1,0]
	v_add_f32_dpp v68, v68, v68 quad_perm:[1,0,3,2] row_mask:0xf bank_mask:0xf bound_ctrl:1
	v_add_f32_dpp v70, v70, v70 quad_perm:[1,0,3,2] row_mask:0xf bank_mask:0xf bound_ctrl:1
	v_pk_mul_f32 v[78:79], v[30:31], v[40:41] op_sel_hi:[1,0]
	v_pk_mul_f32 v[82:83], v[30:31], v[42:43] op_sel_hi:[1,0]
	v_add_f32_dpp v68, v68, v68 quad_perm:[2,3,0,1] row_mask:0xf bank_mask:0xf bound_ctrl:1
	v_add_f32_dpp v70, v70, v70 quad_perm:[2,3,0,1] row_mask:0xf bank_mask:0xf bound_ctrl:1
	v_pk_fma_f32 v[76:77], v[128:129], v[24:25], v[76:77]
	v_pk_fma_f32 v[80:81], v[16:17], v[24:25], v[80:81]
	v_add_f32_dpp v68, v68, v68 row_half_mirror row_mask:0xf bank_mask:0xf bound_ctrl:1
	v_add_f32_dpp v70, v70, v70 row_half_mirror row_mask:0xf bank_mask:0xf bound_ctrl:1
	v_pk_fma_f32 v[78:79], v[130:131], v[26:27], v[78:79]
	v_pk_fma_f32 v[82:83], v[14:15], v[26:27], v[82:83]
	v_add_f32_dpp v68, v68, v68 row_mirror row_mask:0xf bank_mask:0xf bound_ctrl:1
	v_add_f32_dpp v70, v70, v70 row_mirror row_mask:0xf bank_mask:0xf bound_ctrl:1
	v_pk_fma_f32 v[128:129], v[36:37], v[68:69], v[76:77] op_sel_hi:[1,0,1]
	v_pk_fma_f32 v[16:17], v[36:37], v[70:71], v[80:81] op_sel_hi:[1,0,1]
	v_pk_fma_f32 v[130:131], v[38:39], v[68:69], v[78:79] op_sel_hi:[1,0,1]
	v_pk_fma_f32 v[14:15], v[38:39], v[70:71], v[82:83] op_sel_hi:[1,0,1]
	v_pk_mul_f32 v[84:85], v[128:129], v[20:21]
	v_pk_mul_f32 v[86:87], v[16:17], v[20:21]
	v_pk_fma_f32 v[84:85], v[130:131], v[22:23], v[84:85]
	v_pk_fma_f32 v[86:87], v[14:15], v[22:23], v[86:87]
	v_add_f32_e32 v102, v84, v85
	v_add_f32_e32 v132, v86, v87
	s_waitcnt lgkmcnt(0)
; DI float dpp_xor1(float x) { return __int_as_float(__builtin_amdgcn_mov_dpp(__float_as_int(x), 0xB1, 0xF, 0xF, true)); }
; DI float dpp_xor2(float x) { return __int_as_float(__builtin_amdgcn_mov_dpp(__float_as_int(x), 0x4E, 0xF, 0xF, true)); }
; DI float dpp_hm(float x) { return __int_as_float(__builtin_amdgcn_mov_dpp(__float_as_int(x), 0x141, 0xF, 0xF, true)); }
; DI float dpp_rm(float x) { return __int_as_float(__builtin_amdgcn_mov_dpp(__float_as_int(x), 0x140, 0xF, 0xF, true)); }
; DI void rwkv_scan_task(const Params& p, const Grp& G, int unit, char* lds) {
;     ...
;       for (int st = 0; st < 16; ++st) {
;         float4 kkB = kkA, wB = wA, kaB = kaA, kdB = kdA, rrB = rrA;
;         float vvB = vvA, uuB = uuA;
;         if (st < 15) {
;           const float* b = cur + (st + 1) * 384 + part * 4;
;           kkB = *(const float4*)(b + 3 * 64); wB = *(const float4*)(b + 1 * 64); kaB = *(const float4*)(b + 4 * 64);
;           kdB = *(const float4*)(b + 2 * 64); rrB = *(const float4*)(b);
;           vvB = cur[(st + 1) * 384 + 5 * 64 + vrow];
;           uuB = cur[(st + 1) * 384 + 5 * 64 + vrow + 4];
;         }
;         float ra = (S0 * kkA.x + S1 * kkA.y) + (S2 * kkA.z + S3 * kkA.w);
;         float rb = (T0 * kkA.x + T1 * kkA.y) + (T2 * kkA.z + T3 * kkA.w);
;         float rc = ypA, rd = ypB;
;         ra += dpp_xor1(ra); rb += dpp_xor1(rb); rc += dpp_xor1(rc); rd += dpp_xor1(rd);
;         ra += dpp_xor2(ra); rb += dpp_xor2(rb); rc += dpp_xor2(rc); rd += dpp_xor2(rd);
;         ra += dpp_hm(ra); rb += dpp_hm(rb); rc += dpp_hm(rc); rd += dpp_hm(rd);
;         ra += dpp_rm(ra); rb += dpp_rm(rb); rc += dpp_rm(rc); rd += dpp_rm(rd);
;         if (st > 0) { ykeep = (part == st - 1) ? rc : ykeep; zkeep = (part == st - 1) ? rd : zkeep; }
;         const float sa = ra, sb = rb;
;         S0 = S0 * wA.x + (sa * kaA.x + vvA * kdA.x);
;         S1 = S1 * wA.y + (sa * kaA.y + vvA * kdA.y);
;         S2 = S2 * wA.z + (sa * kaA.z + vvA * kdA.z);
;         S3 = S3 * wA.w + (sa * kaA.w + vvA * kdA.w);
;         T0 = T0 * wA.x + (sb * kaA.x + uuA * kdA.x);
;         T1 = T1 * wA.y + (sb * kaA.y + uuA * kdA.y);
;         T2 = T2 * wA.z + (sb * kaA.z + uuA * kdA.z);
;         T3 = T3 * wA.w + (sb * kaA.w + uuA * kdA.w);
;         ypA = (S0 * rrA.x + S1 * rrA.y) + (S2 * rrA.z + S3 * rrA.w);
;         ypB = (T0 * rrA.x + T1 * rrA.y) + (T2 * rrA.z + T3 * rrA.w);
	ds_read_b128 v[32:35], v18 offset:19200
	ds_read_b128 v[28:31], v18 offset:18944
	ds_read_b32 v40, v152 offset:19712
	ds_read_b32 v42, v152 offset:19728
	ds_read_b128 v[24:27], v18 offset:18688
	ds_read_b128 v[36:39], v18 offset:19456
	ds_read_b128 v[20:23], v18 offset:18432
	v_pk_mul_f32 v[84:85], v[128:129], v[56:57]
	v_pk_mul_f32 v[86:87], v[16:17], v[56:57]
	v_pk_fma_f32 v[84:85], v[130:131], v[58:59], v[84:85]
	v_pk_fma_f32 v[86:87], v[14:15], v[58:59], v[86:87]
	v_add_f32_e32 v68, v84, v85
	v_add_f32_e32 v70, v86, v87
	v_pk_mul_f32 v[76:77], v[52:53], v[64:65] op_sel_hi:[1,0]
	v_pk_mul_f32 v[80:81], v[52:53], v[66:67] op_sel_hi:[1,0]
	v_add_f32_dpp v68, v68, v68 quad_perm:[1,0,3,2] row_mask:0xf bank_mask:0xf bound_ctrl:1
	v_add_f32_dpp v70, v70, v70 quad_perm:[1,0,3,2] row_mask:0xf bank_mask:0xf bound_ctrl:1
	v_pk_mul_f32 v[78:79], v[54:55], v[64:65] op_sel_hi:[1,0]
	v_pk_mul_f32 v[82:83], v[54:55], v[66:67] op_sel_hi:[1,0]
	v_add_f32_dpp v68, v68, v68 quad_perm:[2,3,0,1] row_mask:0xf bank_mask:0xf bound_ctrl:1
	v_add_f32_dpp v70, v70, v70 quad_perm:[2,3,0,1] row_mask:0xf bank_mask:0xf bound_ctrl:1
	v_pk_fma_f32 v[76:77], v[128:129], v[48:49], v[76:77]
	v_pk_fma_f32 v[80:81], v[16:17], v[48:49], v[80:81]
	v_add_f32_dpp v68, v68, v68 row_half_mirror row_mask:0xf bank_mask:0xf bound_ctrl:1
	v_add_f32_dpp v70, v70, v70 row_half_mirror row_mask:0xf bank_mask:0xf bound_ctrl:1
	v_pk_fma_f32 v[78:79], v[130:131], v[50:51], v[78:79]
	v_pk_fma_f32 v[82:83], v[14:15], v[50:51], v[82:83]
	v_add_f32_dpp v68, v68, v68 row_mirror row_mask:0xf bank_mask:0xf bound_ctrl:1
	v_add_f32_dpp v70, v70, v70 row_mirror row_mask:0xf bank_mask:0xf bound_ctrl:1
	v_pk_fma_f32 v[128:129], v[60:61], v[68:69], v[76:77] op_sel_hi:[1,0,1]
	v_pk_fma_f32 v[16:17], v[60:61], v[70:71], v[80:81] op_sel_hi:[1,0,1]
	v_pk_fma_f32 v[130:131], v[62:63], v[68:69], v[78:79] op_sel_hi:[1,0,1]
	v_pk_fma_f32 v[14:15], v[62:63], v[70:71], v[82:83] op_sel_hi:[1,0,1]
	v_pk_mul_f32 v[84:85], v[128:129], v[44:45]
	v_pk_mul_f32 v[86:87], v[16:17], v[44:45]
	v_pk_fma_f32 v[84:85], v[130:131], v[46:47], v[84:85]
	v_pk_fma_f32 v[86:87], v[14:15], v[46:47], v[86:87]
	v_add_f32_e32 v103, v84, v85
	v_add_f32_e32 v133, v86, v87
	s_waitcnt lgkmcnt(0)
	ds_read_b128 v[56:59], v18 offset:20736
	ds_read_b128 v[52:55], v18 offset:20480
	ds_read_b32 v64, v152 offset:21248
	ds_read_b32 v66, v152 offset:21264
	ds_read_b128 v[48:51], v18 offset:20224
	ds_read_b128 v[60:63], v18 offset:20992
	ds_read_b128 v[44:47], v18 offset:19968
	v_pk_mul_f32 v[84:85], v[128:129], v[32:33]
	v_pk_mul_f32 v[86:87], v[16:17], v[32:33]
	v_pk_fma_f32 v[84:85], v[130:131], v[34:35], v[84:85]
	v_pk_fma_f32 v[86:87], v[14:15], v[34:35], v[86:87]
	v_add_f32_e32 v68, v84, v85
	v_add_f32_e32 v70, v86, v87
	v_pk_mul_f32 v[76:77], v[28:29], v[40:41] op_sel_hi:[1,0]
	v_pk_mul_f32 v[80:81], v[28:29], v[42:43] op_sel_hi:[1,0]
	v_add_f32_dpp v68, v68, v68 quad_perm:[1,0,3,2] row_mask:0xf bank_mask:0xf bound_ctrl:1
	v_add_f32_dpp v70, v70, v70 quad_perm:[1,0,3,2] row_mask:0xf bank_mask:0xf bound_ctrl:1
	v_pk_mul_f32 v[78:79], v[30:31], v[40:41] op_sel_hi:[1,0]
	v_pk_mul_f32 v[82:83], v[30:31], v[42:43] op_sel_hi:[1,0]
	v_add_f32_dpp v68, v68, v68 quad_perm:[2,3,0,1] row_mask:0xf bank_mask:0xf bound_ctrl:1
	v_add_f32_dpp v70, v70, v70 quad_perm:[2,3,0,1] row_mask:0xf bank_mask:0xf bound_ctrl:1
	v_pk_fma_f32 v[76:77], v[128:129], v[24:25], v[76:77]
	v_pk_fma_f32 v[80:81], v[16:17], v[24:25], v[80:81]
	v_add_f32_dpp v68, v68, v68 row_half_mirror row_mask:0xf bank_mask:0xf bound_ctrl:1
	v_add_f32_dpp v70, v70, v70 row_half_mirror row_mask:0xf bank_mask:0xf bound_ctrl:1
	v_pk_fma_f32 v[78:79], v[130:131], v[26:27], v[78:79]
	v_pk_fma_f32 v[82:83], v[14:15], v[26:27], v[82:83]
	v_add_f32_dpp v68, v68, v68 row_mirror row_mask:0xf bank_mask:0xf bound_ctrl:1
	v_add_f32_dpp v70, v70, v70 row_mirror row_mask:0xf bank_mask:0xf bound_ctrl:1
	v_pk_fma_f32 v[128:129], v[36:37], v[68:69], v[76:77] op_sel_hi:[1,0,1]
	v_pk_fma_f32 v[16:17], v[36:37], v[70:71], v[80:81] op_sel_hi:[1,0,1]
	v_pk_fma_f32 v[130:131], v[38:39], v[68:69], v[78:79] op_sel_hi:[1,0,1]
	v_pk_fma_f32 v[14:15], v[38:39], v[70:71], v[82:83] op_sel_hi:[1,0,1]
	v_pk_mul_f32 v[84:85], v[128:129], v[20:21]
	v_pk_mul_f32 v[86:87], v[16:17], v[20:21]
	v_pk_fma_f32 v[84:85], v[130:131], v[22:23], v[84:85]
	v_pk_fma_f32 v[86:87], v[14:15], v[22:23], v[86:87]
	v_add_f32_e32 v104, v84, v85
	v_add_f32_e32 v134, v86, v87
	s_waitcnt lgkmcnt(0)
	ds_read_b128 v[32:35], v18 offset:22272
	ds_read_b128 v[28:31], v18 offset:22016
	ds_read_b32 v40, v152 offset:22784
	ds_read_b32 v42, v152 offset:22800
	ds_read_b128 v[24:27], v18 offset:21760
	ds_read_b128 v[36:39], v18 offset:22528
	ds_read_b128 v[20:23], v18 offset:21504
	v_pk_mul_f32 v[84:85], v[128:129], v[56:57]
	v_pk_mul_f32 v[86:87], v[16:17], v[56:57]
	v_pk_fma_f32 v[84:85], v[130:131], v[58:59], v[84:85]
	v_pk_fma_f32 v[86:87], v[14:15], v[58:59], v[86:87]
	v_add_f32_e32 v68, v84, v85
	v_add_f32_e32 v70, v86, v87
	v_pk_mul_f32 v[76:77], v[52:53], v[64:65] op_sel_hi:[1,0]
	v_pk_mul_f32 v[80:81], v[52:53], v[66:67] op_sel_hi:[1,0]
	v_add_f32_dpp v68, v68, v68 quad_perm:[1,0,3,2] row_mask:0xf bank_mask:0xf bound_ctrl:1
	v_add_f32_dpp v70, v70, v70 quad_perm:[1,0,3,2] row_mask:0xf bank_mask:0xf bound_ctrl:1
	v_pk_mul_f32 v[78:79], v[54:55], v[64:65] op_sel_hi:[1,0]
	v_pk_mul_f32 v[82:83], v[54:55], v[66:67] op_sel_hi:[1,0]
	v_add_f32_dpp v68, v68, v68 quad_perm:[2,3,0,1] row_mask:0xf bank_mask:0xf bound_ctrl:1
	v_add_f32_dpp v70, v70, v70 quad_perm:[2,3,0,1] row_mask:0xf bank_mask:0xf bound_ctrl:1
	v_pk_fma_f32 v[76:77], v[128:129], v[48:49], v[76:77]
	v_pk_fma_f32 v[80:81], v[16:17], v[48:49], v[80:81]
	v_add_f32_dpp v68, v68, v68 row_half_mirror row_mask:0xf bank_mask:0xf bound_ctrl:1
	v_add_f32_dpp v70, v70, v70 row_half_mirror row_mask:0xf bank_mask:0xf bound_ctrl:1
	v_pk_fma_f32 v[78:79], v[130:131], v[50:51], v[78:79]
	v_pk_fma_f32 v[82:83], v[14:15], v[50:51], v[82:83]
	v_add_f32_dpp v68, v68, v68 row_mirror row_mask:0xf bank_mask:0xf bound_ctrl:1
	v_add_f32_dpp v70, v70, v70 row_mirror row_mask:0xf bank_mask:0xf bound_ctrl:1
	v_pk_fma_f32 v[128:129], v[60:61], v[68:69], v[76:77] op_sel_hi:[1,0,1]
	v_pk_fma_f32 v[16:17], v[60:61], v[70:71], v[80:81] op_sel_hi:[1,0,1]
	v_pk_fma_f32 v[130:131], v[62:63], v[68:69], v[78:79] op_sel_hi:[1,0,1]
	v_pk_fma_f32 v[14:15], v[62:63], v[70:71], v[82:83] op_sel_hi:[1,0,1]
	v_pk_mul_f32 v[84:85], v[128:129], v[44:45]
	v_pk_mul_f32 v[86:87], v[16:17], v[44:45]
	v_pk_fma_f32 v[84:85], v[130:131], v[46:47], v[84:85]
	v_pk_fma_f32 v[86:87], v[14:15], v[46:47], v[86:87]
	v_add_f32_e32 v105, v84, v85
	v_add_f32_e32 v135, v86, v87
	s_waitcnt lgkmcnt(0)
; DI float dpp_xor1(float x) { return __int_as_float(__builtin_amdgcn_mov_dpp(__float_as_int(x), 0xB1, 0xF, 0xF, true)); }
; DI float dpp_xor2(float x) { return __int_as_float(__builtin_amdgcn_mov_dpp(__float_as_int(x), 0x4E, 0xF, 0xF, true)); }
; DI void rwkv_scan_task(const Params& p, const Grp& G, int unit, char* lds) {
;     ...
;       for (int st = 0; st < 16; ++st) {
;         float4 kkB = kkA, wB = wA, kaB = kaA, kdB = kdA, rrB = rrA;
;         float vvB = vvA, uuB = uuA;
;         if (st < 15) {
;           const float* b = cur + (st + 1) * 384 + part * 4;
;           kkB = *(const float4*)(b + 3 * 64); wB = *(const float4*)(b + 1 * 64); kaB = *(const float4*)(b + 4 * 64);
;           kdB = *(const float4*)(b + 2 * 64); rrB = *(const float4*)(b);
;           vvB = cur[(st + 1) * 384 + 5 * 64 + vrow];
;           uuB = cur[(st + 1) * 384 + 5 * 64 + vrow + 4];
;         }
;         float ra = (S0 * kkA.x + S1 * kkA.y) + (S2 * kkA.z + S3 * kkA.w);
;         float rb = (T0 * kkA.x + T1 * kkA.y) + (T2 * kkA.z + T3 * kkA.w);
;         float rc = ypA, rd = ypB;
;         ra += dpp_xor1(ra); rb += dpp_xor1(rb); rc += dpp_xor1(rc); rd += dpp_xor1(rd);
;         ra += dpp_xor2(ra); rb += dpp_xor2(rb); rc += dpp_xor2(rc); rd += dpp_xor2(rd);
;         ra += dpp_hm(ra); rb += dpp_hm(rb); rc += dpp_hm(rc); rd += dpp_hm(rd);
;         ra += dpp_rm(ra); rb += dpp_rm(rb); rc += dpp_rm(rc); rd += dpp_rm(rd);
;         if (st > 0) { ykeep = (part == st - 1) ? rc : ykeep; zkeep = (part == st - 1) ? rd : zkeep; }
;         const float sa = ra, sb = rb;
;         S0 = S0 * wA.x + (sa * kaA.x + vvA * kdA.x);
;         S1 = S1 * wA.y + (sa * kaA.y + vvA * kdA.y);
;         S2 = S2 * wA.z + (sa * kaA.z + vvA * kdA.z);
;         S3 = S3 * wA.w + (sa * kaA.w + vvA * kdA.w);
;         T0 = T0 * wA.x + (sb * kaA.x + uuA * kdA.x);
;         T1 = T1 * wA.y + (sb * kaA.y + uuA * kdA.y);
;         T2 = T2 * wA.z + (sb * kaA.z + uuA * kdA.z);
;         T3 = T3 * wA.w + (sb * kaA.w + uuA * kdA.w);
;         ypA = (S0 * rrA.x + S1 * rrA.y) + (S2 * rrA.z + S3 * rrA.w);
;         ypB = (T0 * rrA.x + T1 * rrA.y) + (T2 * rrA.z + T3 * rrA.w);
;         kkA = kkB; wA = wB; kaA = kaB; kdA = kdB; rrA = rrB; vvA = vvB; uuA = uuB;
;       }
;       {
;         float y15 = row16_sum(ypA), z15 = row16_sum(ypB);
;         ykeep = (part == 15) ? y15 : ykeep; zkeep = (part == 15) ? z15 : zkeep;
	ds_read_b128 v[56:59], v18 offset:23808
	ds_read_b128 v[52:55], v18 offset:23552
	ds_read_b32 v64, v152 offset:24320
	ds_read_b32 v66, v152 offset:24336
	ds_read_b128 v[48:51], v18 offset:23296
	ds_read_b128 v[60:63], v18 offset:24064
	ds_read_b128 v[44:47], v18 offset:23040
	v_pk_mul_f32 v[84:85], v[128:129], v[32:33]
	v_pk_mul_f32 v[86:87], v[16:17], v[32:33]
	v_pk_fma_f32 v[84:85], v[130:131], v[34:35], v[84:85]
	v_pk_fma_f32 v[86:87], v[14:15], v[34:35], v[86:87]
	v_add_f32_e32 v68, v84, v85
	v_add_f32_e32 v70, v86, v87
	v_pk_mul_f32 v[76:77], v[28:29], v[40:41] op_sel_hi:[1,0]
	v_pk_mul_f32 v[80:81], v[28:29], v[42:43] op_sel_hi:[1,0]
	v_add_f32_dpp v68, v68, v68 quad_perm:[1,0,3,2] row_mask:0xf bank_mask:0xf bound_ctrl:1
	v_add_f32_dpp v70, v70, v70 quad_perm:[1,0,3,2] row_mask:0xf bank_mask:0xf bound_ctrl:1
	v_pk_mul_f32 v[78:79], v[30:31], v[40:41] op_sel_hi:[1,0]
	v_pk_mul_f32 v[82:83], v[30:31], v[42:43] op_sel_hi:[1,0]
	v_add_f32_dpp v68, v68, v68 quad_perm:[2,3,0,1] row_mask:0xf bank_mask:0xf bound_ctrl:1
	v_add_f32_dpp v70, v70, v70 quad_perm:[2,3,0,1] row_mask:0xf bank_mask:0xf bound_ctrl:1
	v_pk_fma_f32 v[76:77], v[128:129], v[24:25], v[76:77]
	v_pk_fma_f32 v[80:81], v[16:17], v[24:25], v[80:81]
	v_add_f32_dpp v68, v68, v68 row_half_mirror row_mask:0xf bank_mask:0xf bound_ctrl:1
	v_add_f32_dpp v70, v70, v70 row_half_mirror row_mask:0xf bank_mask:0xf bound_ctrl:1
	v_pk_fma_f32 v[78:79], v[130:131], v[26:27], v[78:79]
	v_pk_fma_f32 v[82:83], v[14:15], v[26:27], v[82:83]
	v_add_f32_dpp v68, v68, v68 row_mirror row_mask:0xf bank_mask:0xf bound_ctrl:1
	v_add_f32_dpp v70, v70, v70 row_mirror row_mask:0xf bank_mask:0xf bound_ctrl:1
	v_pk_fma_f32 v[128:129], v[36:37], v[68:69], v[76:77] op_sel_hi:[1,0,1]
	v_pk_fma_f32 v[16:17], v[36:37], v[70:71], v[80:81] op_sel_hi:[1,0,1]
	v_pk_fma_f32 v[130:131], v[38:39], v[68:69], v[78:79] op_sel_hi:[1,0,1]
	v_pk_fma_f32 v[14:15], v[38:39], v[70:71], v[82:83] op_sel_hi:[1,0,1]
	v_pk_mul_f32 v[84:85], v[128:129], v[20:21]
	v_pk_mul_f32 v[86:87], v[16:17], v[20:21]
	v_pk_fma_f32 v[84:85], v[130:131], v[22:23], v[84:85]
	v_pk_fma_f32 v[86:87], v[14:15], v[22:23], v[86:87]
	v_add_f32_e32 v106, v84, v85
	v_add_f32_e32 v136, v86, v87
	s_waitcnt lgkmcnt(0)
	v_pk_mul_f32 v[84:85], v[128:129], v[56:57]
	v_pk_mul_f32 v[86:87], v[16:17], v[56:57]
	v_pk_fma_f32 v[84:85], v[130:131], v[58:59], v[84:85]
	v_pk_fma_f32 v[86:87], v[14:15], v[58:59], v[86:87]
	v_add_f32_e32 v68, v84, v85
	v_add_f32_e32 v70, v86, v87
	v_pk_mul_f32 v[76:77], v[52:53], v[64:65] op_sel_hi:[1,0]
	v_pk_mul_f32 v[80:81], v[52:53], v[66:67] op_sel_hi:[1,0]
	v_add_f32_dpp v68, v68, v68 quad_perm:[1,0,3,2] row_mask:0xf bank_mask:0xf bound_ctrl:1
	v_add_f32_dpp v70, v70, v70 quad_perm:[1,0,3,2] row_mask:0xf bank_mask:0xf bound_ctrl:1
	v_pk_mul_f32 v[78:79], v[54:55], v[64:65] op_sel_hi:[1,0]
	v_pk_mul_f32 v[82:83], v[54:55], v[66:67] op_sel_hi:[1,0]
	v_add_f32_dpp v68, v68, v68 quad_perm:[2,3,0,1] row_mask:0xf bank_mask:0xf bound_ctrl:1
	v_add_f32_dpp v70, v70, v70 quad_perm:[2,3,0,1] row_mask:0xf bank_mask:0xf bound_ctrl:1
	v_pk_fma_f32 v[76:77], v[128:129], v[48:49], v[76:77]
	v_pk_fma_f32 v[80:81], v[16:17], v[48:49], v[80:81]
	v_add_f32_dpp v68, v68, v68 row_half_mirror row_mask:0xf bank_mask:0xf bound_ctrl:1
	v_add_f32_dpp v70, v70, v70 row_half_mirror row_mask:0xf bank_mask:0xf bound_ctrl:1
	v_pk_fma_f32 v[78:79], v[130:131], v[50:51], v[78:79]
	v_pk_fma_f32 v[82:83], v[14:15], v[50:51], v[82:83]
	v_add_f32_dpp v68, v68, v68 row_mirror row_mask:0xf bank_mask:0xf bound_ctrl:1
	v_add_f32_dpp v70, v70, v70 row_mirror row_mask:0xf bank_mask:0xf bound_ctrl:1
	v_pk_fma_f32 v[128:129], v[60:61], v[68:69], v[76:77] op_sel_hi:[1,0,1]
	v_pk_fma_f32 v[16:17], v[60:61], v[70:71], v[80:81] op_sel_hi:[1,0,1]
	v_pk_fma_f32 v[130:131], v[62:63], v[68:69], v[78:79] op_sel_hi:[1,0,1]
	v_pk_fma_f32 v[14:15], v[62:63], v[70:71], v[82:83] op_sel_hi:[1,0,1]
	v_pk_mul_f32 v[84:85], v[128:129], v[44:45]
	v_pk_mul_f32 v[86:87], v[16:17], v[44:45]
	v_pk_fma_f32 v[84:85], v[130:131], v[46:47], v[84:85]
	v_pk_fma_f32 v[86:87], v[14:15], v[46:47], v[86:87]
	v_add_f32_e32 v107, v84, v85
	v_add_f32_e32 v137, v86, v87
	v_add_f32_dpp v92, v92, v92 row_ror:8 row_mask:0xf bank_mask:0x3 bound_ctrl:1
	v_add_f32_dpp v92, v93, v93 row_ror:8 row_mask:0xf bank_mask:0xc bound_ctrl:1
	v_add_f32_dpp v108, v108, v108 row_ror:8 row_mask:0xf bank_mask:0x3 bound_ctrl:1
	v_add_f32_dpp v108, v109, v109 row_ror:8 row_mask:0xf bank_mask:0xc bound_ctrl:1
	v_add_f32_dpp v94, v94, v94 row_ror:8 row_mask:0xf bank_mask:0x3 bound_ctrl:1
	v_add_f32_dpp v94, v95, v95 row_ror:8 row_mask:0xf bank_mask:0xc bound_ctrl:1
	v_add_f32_dpp v110, v110, v110 row_ror:8 row_mask:0xf bank_mask:0x3 bound_ctrl:1
	v_add_f32_dpp v110, v111, v111 row_ror:8 row_mask:0xf bank_mask:0xc bound_ctrl:1
	v_add_f32_dpp v96, v96, v96 row_ror:8 row_mask:0xf bank_mask:0x3 bound_ctrl:1
	v_add_f32_dpp v96, v97, v97 row_ror:8 row_mask:0xf bank_mask:0xc bound_ctrl:1
	v_add_f32_dpp v112, v112, v112 row_ror:8 row_mask:0xf bank_mask:0x3 bound_ctrl:1
	v_add_f32_dpp v112, v113, v113 row_ror:8 row_mask:0xf bank_mask:0xc bound_ctrl:1
	v_add_f32_dpp v98, v98, v98 row_ror:8 row_mask:0xf bank_mask:0x3 bound_ctrl:1
	v_add_f32_dpp v98, v99, v99 row_ror:8 row_mask:0xf bank_mask:0xc bound_ctrl:1
	v_add_f32_dpp v114, v114, v114 row_ror:8 row_mask:0xf bank_mask:0x3 bound_ctrl:1
	v_add_f32_dpp v114, v115, v115 row_ror:8 row_mask:0xf bank_mask:0xc bound_ctrl:1
	v_add_f32_dpp v100, v100, v100 row_ror:8 row_mask:0xf bank_mask:0x3 bound_ctrl:1
	v_add_f32_dpp v100, v101, v101 row_ror:8 row_mask:0xf bank_mask:0xc bound_ctrl:1
; DI bf16_t f2bf(float f) { return (bf16_t)(pack2(f, f) & 0xffffu); }
; DI int otid() { int t = threadIdx.x; asm volatile("" : "+v"(t)); return t; }
; DI float row16_sum(float x) { x += dpp_xor1(x); x += dpp_xor2(x); x += dpp_hm(x); x += dpp_rm(x); return x; }
; DI void rwkv_scan_task(const Params& p, const Grp& G, int unit, char* lds) {
;     ...
;       {
;         float y15 = row16_sum(ypA), z15 = row16_sum(ypB);
;         ykeep = (part == 15) ? y15 : ykeep; zkeep = (part == 15) ? z15 : zkeep;
;         int s = tl * 16 + part, pos = dir ? G.len - 1 - s : s;
;         obase[(size_t)pos * RAWC] = f2bf(ykeep);
;         obase[(size_t)pos * RAWC + 4] = f2bf(zkeep);
; DI void phase_scans(const Params& p, const Grp& G, int layer, char* lds) {
;     ...
;   if (p.nb_pre > 0 || G.sample) {
;     const int tid_ = otid(); const int lane = tid_ & 63, wv = tid_ >> 6, wr = wv >> 1, wc = wv & 1;
;     const int MTn = (G.rows + 255) / 256, NTn = D / 128;
;     const int gate_total = p.nb_pre * MTn * NTn;
;     const int total = gate_total + (G.sample ? MTn * 40 : 0);
;     int* s_t = (int*)(lds + LDS_BYTES - 16);
;     for (;;) {
;       __syncthreads();
;       if (tid_ == 0) *s_t = (int)__hip_atomic_fetch_add(p.qctr, 1u, __ATOMIC_RELAXED, __HIP_MEMORY_SCOPE_AGENT);
	v_add_f32_dpp v116, v116, v116 row_ror:8 row_mask:0xf bank_mask:0x3 bound_ctrl:1
	v_add_f32_dpp v116, v117, v117 row_ror:8 row_mask:0xf bank_mask:0xc bound_ctrl:1
	v_add_f32_dpp v102, v102, v102 row_ror:8 row_mask:0xf bank_mask:0x3 bound_ctrl:1
	v_add_f32_dpp v102, v103, v103 row_ror:8 row_mask:0xf bank_mask:0xc bound_ctrl:1
	v_add_f32_dpp v132, v132, v132 row_ror:8 row_mask:0xf bank_mask:0x3 bound_ctrl:1
	v_add_f32_dpp v132, v133, v133 row_ror:8 row_mask:0xf bank_mask:0xc bound_ctrl:1
	v_add_f32_dpp v104, v104, v104 row_ror:8 row_mask:0xf bank_mask:0x3 bound_ctrl:1
	v_add_f32_dpp v104, v105, v105 row_ror:8 row_mask:0xf bank_mask:0xc bound_ctrl:1
	v_add_f32_dpp v134, v134, v134 row_ror:8 row_mask:0xf bank_mask:0x3 bound_ctrl:1
	v_add_f32_dpp v134, v135, v135 row_ror:8 row_mask:0xf bank_mask:0xc bound_ctrl:1
	v_add_f32_dpp v106, v106, v106 row_ror:8 row_mask:0xf bank_mask:0x3 bound_ctrl:1
	v_add_f32_dpp v106, v107, v107 row_ror:8 row_mask:0xf bank_mask:0xc bound_ctrl:1
	v_add_f32_dpp v136, v136, v136 row_ror:8 row_mask:0xf bank_mask:0x3 bound_ctrl:1
	v_add_f32_dpp v136, v137, v137 row_ror:8 row_mask:0xf bank_mask:0xc bound_ctrl:1
	v_add_f32_dpp v92, v92, v92 row_shl:4 row_mask:0xf bank_mask:0x5 bound_ctrl:1
	v_add_f32_dpp v92, v94, v94 row_shr:4 row_mask:0xf bank_mask:0xa bound_ctrl:1
	v_add_f32_dpp v108, v108, v108 row_shl:4 row_mask:0xf bank_mask:0x5 bound_ctrl:1
	v_add_f32_dpp v108, v110, v110 row_shr:4 row_mask:0xf bank_mask:0xa bound_ctrl:1
	v_add_f32_dpp v96, v96, v96 row_shl:4 row_mask:0xf bank_mask:0x5 bound_ctrl:1
	v_add_f32_dpp v96, v98, v98 row_shr:4 row_mask:0xf bank_mask:0xa bound_ctrl:1
	v_add_f32_dpp v112, v112, v112 row_shl:4 row_mask:0xf bank_mask:0x5 bound_ctrl:1
	v_add_f32_dpp v112, v114, v114 row_shr:4 row_mask:0xf bank_mask:0xa bound_ctrl:1
	v_add_f32_dpp v100, v100, v100 row_shl:4 row_mask:0xf bank_mask:0x5 bound_ctrl:1
	v_add_f32_dpp v100, v102, v102 row_shr:4 row_mask:0xf bank_mask:0xa bound_ctrl:1
	v_add_f32_dpp v116, v116, v116 row_shl:4 row_mask:0xf bank_mask:0x5 bound_ctrl:1
	v_add_f32_dpp v116, v132, v132 row_shr:4 row_mask:0xf bank_mask:0xa bound_ctrl:1
	v_add_f32_dpp v104, v104, v104 row_shl:4 row_mask:0xf bank_mask:0x5 bound_ctrl:1
	v_add_f32_dpp v104, v106, v106 row_shr:4 row_mask:0xf bank_mask:0xa bound_ctrl:1
	v_add_f32_dpp v134, v134, v134 row_shl:4 row_mask:0xf bank_mask:0x5 bound_ctrl:1
	v_add_f32_dpp v134, v136, v136 row_shr:4 row_mask:0xf bank_mask:0xa bound_ctrl:1
	v_add_f32_dpp v92, v92, v92 quad_perm:[1,0,3,2] row_mask:0xf bank_mask:0xf bound_ctrl:1
	v_add_f32_dpp v108, v108, v108 quad_perm:[1,0,3,2] row_mask:0xf bank_mask:0xf bound_ctrl:1
	v_add_f32_dpp v96, v96, v96 quad_perm:[1,0,3,2] row_mask:0xf bank_mask:0xf bound_ctrl:1
	v_add_f32_dpp v112, v112, v112 quad_perm:[1,0,3,2] row_mask:0xf bank_mask:0xf bound_ctrl:1
	v_add_f32_dpp v100, v100, v100 quad_perm:[1,0,3,2] row_mask:0xf bank_mask:0xf bound_ctrl:1
	v_add_f32_dpp v116, v116, v116 quad_perm:[1,0,3,2] row_mask:0xf bank_mask:0xf bound_ctrl:1
	v_add_f32_dpp v104, v104, v104 quad_perm:[1,0,3,2] row_mask:0xf bank_mask:0xf bound_ctrl:1
	v_add_f32_dpp v134, v134, v134 quad_perm:[1,0,3,2] row_mask:0xf bank_mask:0xf bound_ctrl:1
	v_add_f32_dpp v92, v92, v92 quad_perm:[2,3,0,1] row_mask:0xf bank_mask:0xf bound_ctrl:1
	v_add_f32_dpp v108, v108, v108 quad_perm:[2,3,0,1] row_mask:0xf bank_mask:0xf bound_ctrl:1
	v_add_f32_dpp v96, v96, v96 quad_perm:[2,3,0,1] row_mask:0xf bank_mask:0xf bound_ctrl:1
	v_add_f32_dpp v112, v112, v112 quad_perm:[2,3,0,1] row_mask:0xf bank_mask:0xf bound_ctrl:1
	v_add_f32_dpp v100, v100, v100 quad_perm:[2,3,0,1] row_mask:0xf bank_mask:0xf bound_ctrl:1
	v_add_f32_dpp v116, v116, v116 quad_perm:[2,3,0,1] row_mask:0xf bank_mask:0xf bound_ctrl:1
	v_add_f32_dpp v104, v104, v104 quad_perm:[2,3,0,1] row_mask:0xf bank_mask:0xf bound_ctrl:1
	v_add_f32_dpp v134, v134, v134 quad_perm:[2,3,0,1] row_mask:0xf bank_mask:0xf bound_ctrl:1
	v_and_b32_e32 v84, 3, v145
	v_bfe_u32 v85, v145, 2, 1
	v_lshrrev_b32_e32 v86, 3, v145
	v_lshl_add_u32 v87, v85, 1, v86
	v_lshl_add_u32 v87, v84, 2, v87
	v_sub_u32_e32 v85, v145, v87
	v_add_u32_e32 v85, v0, v85
	v_add_u32_e32 v90, s40, v87
	v_cndmask_b32_e64 v90, v85, v90, s[4:5]
	v_ashrrev_i32_e32 v91, 31, v90
	v_lshlrev_b64 v[90:91], 13, v[90:91]
	v_lshl_add_u64 v[90:91], v[120:121], 0, v[90:91]
	v_cmp_lt_u32_e32 vcc, 0, v84
	s_nop 1
	v_cndmask_b32_e32 v92, v92, v96, vcc
	v_cndmask_b32_e32 v108, v108, v112, vcc
	v_cmp_lt_u32_e32 vcc, 1, v84
	s_nop 1
	v_cndmask_b32_e32 v92, v92, v100, vcc
	v_cndmask_b32_e32 v108, v108, v116, vcc
	v_cmp_lt_u32_e32 vcc, 2, v84
	s_nop 1
	v_cndmask_b32_e32 v92, v92, v104, vcc
	v_cndmask_b32_e32 v108, v108, v134, vcc
	v_cvt_pk_bf16_f32 v88, v92, v92
	v_cvt_pk_bf16_f32 v89, v108, v108
	s_andn2_b64 vcc, exec, s[0:1]
	global_store_short v[90:91], v88, off
	global_store_short v[90:91], v89, off offset:8
	s_cbranch_vccnz .LBB0_924
	s_bitcmp1_b32 s41, 0
	s_cselect_b32 s0, 0x6000, 0
	v_lshl_add_u32 v22, v143, 2, s0
	s_waitcnt vmcnt(4)
	v_lshlrev_b32_e32 v18, 16, v2
	v_and_b32_e32 v19, 0xffff0000, v2
	v_lshlrev_b32_e32 v20, 16, v3
	v_and_b32_e32 v21, 0xffff0000, v3
	ds_write_b128 v22, v[18:21]
	v_lshlrev_b32_e32 v18, 16, v4
	v_and_b32_e32 v19, 0xffff0000, v4
	v_lshlrev_b32_e32 v20, 16, v5
	v_and_b32_e32 v21, 0xffff0000, v5
	ds_write_b128 v22, v[18:21] offset:16
	v_lshl_add_u32 v22, v142, 2, s0
	s_waitcnt vmcnt(3)
	v_lshlrev_b32_e32 v18, 16, v6
	v_and_b32_e32 v19, 0xffff0000, v6
	v_lshlrev_b32_e32 v20, 16, v7
	v_and_b32_e32 v21, 0xffff0000, v7
	ds_write_b128 v22, v[18:21]
	v_lshlrev_b32_e32 v18, 16, v8
	v_and_b32_e32 v19, 0xffff0000, v8
	v_lshlrev_b32_e32 v20, 16, v9
	v_and_b32_e32 v21, 0xffff0000, v9
	ds_write_b128 v22, v[18:21] offset:16
	v_lshl_add_u32 v22, v144, 2, s0
	s_waitcnt vmcnt(2)
	v_lshlrev_b32_e32 v18, 16, v10
	v_and_b32_e32 v19, 0xffff0000, v10
	v_lshlrev_b32_e32 v20, 16, v11
	v_and_b32_e32 v21, 0xffff0000, v11
	ds_write_b128 v22, v[18:21]
	v_lshlrev_b32_e32 v18, 16, v12
	v_and_b32_e32 v19, 0xffff0000, v12
	v_lshlrev_b32_e32 v20, 16, v13
	v_and_b32_e32 v21, 0xffff0000, v13
	ds_write_b128 v22, v[18:21] offset:16
	s_branch .LBB0_924
.LBB0_929:
	v_readlane_b32 s0, v254, 21
	v_readlane_b32 s1, v254, 55
	s_cmp_lg_u32 s1, 320
	s_cbranch_scc1 .Lmy_qp_skip
	s_cmp_lt_u32 s0, 384
	s_cbranch_scc1 .Lmy_qp_skip
	s_setprio 1

; DI unsigned xb_add(unsigned* p, unsigned v) { return __hip_atomic_fetch_add(p, v, __ATOMIC_RELAXED, __HIP_MEMORY_SCOPE_AGENT); }
; DI void xcd_barrier(unsigned* bar, const uint4* sh) {
;   asm volatile("s_waitcnt vmcnt(0)" ::: "memory");
;   __syncthreads();
;   if (threadIdx.x == 0) {
;     const uint4 t = *sh;
;     const unsigned bx = t.x, nloc = t.y, nx = t.z;
;     __builtin_amdgcn_s_waitcnt(0);
;     const unsigned old = xb_add(&bar[XB_XSUB(bx)], 1u);
;     const unsigned gen = old / nloc;
;     if (old + 1u == (gen + 1u) * nloc) {
;       __builtin_amdgcn_fence(__ATOMIC_RELEASE, "agent");
;       asm volatile("s_waitcnt vmcnt(0)" ::: "memory");
.LBB0_1112:
	s_setprio 0
	s_waitcnt vmcnt(0)
	s_waitcnt vmcnt(0) lgkmcnt(0)
	s_barrier
	s_mov_b64 s[0:1], exec
	v_readlane_b32 s4, v253, 36
	v_readlane_b32 s5, v253, 37
	s_and_b64 s[4:5], s[0:1], s[4:5]
	s_mov_b64 exec, s[4:5]
	s_cbranch_execz .LBB0_1149
	v_mov_b32_e32 v0, 0x13800
	ds_read_b96 v[2:4], v0
	s_mov_b64 s[4:5], exec
	v_mbcnt_lo_u32_b32 v0, s4, 0
	v_mbcnt_hi_u32_b32 v0, s5, v0
	v_cmp_eq_u32_e32 vcc, 0, v0
	s_waitcnt lgkmcnt(0)
	v_readfirstlane_b32 s2, v2
	s_lshl_b32 s20, s2, 6
	s_waitcnt vmcnt(0) expcnt(0) lgkmcnt(0)
	s_and_saveexec_b64 s[6:7], vcc
	s_cbranch_execz .LBB0_1115
	s_add_i32 s2, s20, 0x500
	v_readlane_b32 s12, v254, 9
	s_lshl_b64 s[8:9], s[2:3], 2
	v_readlane_b32 s16, v254, 13
	v_readlane_b32 s17, v254, 14
	s_add_u32 s8, s16, s8
	s_addc_u32 s9, s17, s9
	s_bcnt1_i32_b64 s2, s[4:5]
	v_mov_b32_e32 v2, s2
	global_atomic_add v2, v1, v2, s[8:9] sc0
	v_readlane_b32 s13, v254, 10
	v_readlane_b32 s14, v254, 11
	v_readlane_b32 s15, v254, 12
	v_readlane_b32 s18, v254, 15
	v_readlane_b32 s19, v254, 16
